# carry computed redundantly per XCD (8 WGs each, storing only the entries that XCD's finish units read) so the post-carry barrier is XCD-local
# speedup vs baseline: 1.0118x; 1.0074x over previous
; __device__ __forceinline__ void carry_phase(const Args& a, int bx) {
;     int tid_ = threadIdx.x; asm volatile("" : "+v"(tid_));
;     const int gt = bx * NTHR + tid_;
;     if (gt >= NB * 2 * LW) return;
;     const int b = gt >> 10, dir = (gt >> 9) & 1, c = gt & 511;
;     const f32x2* tot = (const f32x2*)(a.ws + WS_TOT); float* car = (float*)(a.ws + WS_CAR);
;     float hc = 0.f;
; #pragma unroll 1
;     for (int j0 = 0; j0 < NCH; j0 += 32) {
;         f32x2 v[32];
; #pragma unroll
;         for (int i = 0; i < 32; ++i) { const int j = j0 + i, cj = dir == 0 ? j : NCH - 1 - j; v[i] = tot[(size_t)((b * NCH + cj) * 2 + dir) * LW + c]; }
; #pragma unroll
;         for (int i = 0; i < 32; ++i) { const int j = j0 + i, cj = dir == 0 ? j : NCH - 1 - j; car[(size_t)((b * NCH + cj) * 2 + dir) * LW + c] = hc; hc = v[i].x * hc + v[i].y; }
;     }
; }
.LBB0_252:
	s_or_b64 exec, exec, s[0:1]
	s_waitcnt lgkmcnt(0)
	v_mov_b32_e32 v2, v226
	s_lshr_b32 s0, s2, 3
	s_lshl_b32 s0, s0, 9
	s_barrier
	s_nop 0
	v_add_u32_e32 v0, s0, v2
	s_movk_i32 s0, 0x1000
	v_cmp_gt_i32_e32 vcc, s0, v0
	s_and_saveexec_b64 s[0:1], vcc
	s_xor_b64 s[0:1], exec, s[0:1]
	s_cbranch_execz .LBB0_255
	v_mov_b32_e32 v5, 0x2000c
	ds_read_b32 v5, v5
	s_and_b32 s28, s2, 7
	s_lshr_b32 s29, s2, 3
	s_and_b32 s29, s29, 1
	s_cmp_eq_u32 s29, 0
	s_cbranch_scc1 .Lcar_fwd
	s_sub_i32 s28, 7, s28
.Lcar_fwd:
	s_lshl_b32 s28, 1, s28
	s_waitcnt lgkmcnt(0)
	v_readfirstlane_b32 s29, v5
	s_cmp_eq_u32 s29, 0
	s_cbranch_scc1 .Lcar_m
	s_movk_i32 s28, 0xff
.Lcar_m:
	v_bfe_u32 v3, v0, 9, 1
	v_and_b32_e32 v4, 0x1ff, v2
	v_ashrrev_i32_e32 v0, 2, v0
	s_movk_i32 s29, 0xff00
	v_and_or_b32 v120, v0, s29, v3
	v_readlane_b32 s4, v253, 35
	v_readlane_b32 s5, v253, 36
	v_lshl_add_u32 v5, v120, 9, v4
	v_cmp_eq_u32_e32 vcc, 0, v3
	v_lshlrev_b32_e32 v6, 3, v5
	v_lshlrev_b32_e32 v7, 2, v5
	v_mov_b32_e32 v8, 0xffffe000
	v_mov_b32_e32 v9, 0x2000
	v_cndmask_b32_e32 v8, v8, v9, vcc
	v_mov_b32_e32 v10, 0xfffff000
	v_mov_b32_e32 v11, 0x1000
	v_cndmask_b32_e32 v10, v10, v11, vcc
	v_mov_b32_e32 v12, 0xfe000
	v_cndmask_b32_e64 v12, v12, 0, vcc
	v_add_u32_e32 v6, v6, v12
	v_mov_b32_e32 v12, 0x7f000
	v_cndmask_b32_e64 v12, v12, 0, vcc
	v_add_u32_e32 v7, v7, v12
	v_mov_b32_e32 v13, 0
	global_load_dwordx2 v[14:15], v6, s[74:75]
	v_add_u32_e32 v6, v6, v8
	global_load_dwordx2 v[16:17], v6, s[74:75]
	v_add_u32_e32 v6, v6, v8
	global_load_dwordx2 v[18:19], v6, s[74:75]
	v_add_u32_e32 v6, v6, v8
	global_load_dwordx2 v[20:21], v6, s[74:75]
	v_add_u32_e32 v6, v6, v8
	global_load_dwordx2 v[22:23], v6, s[74:75]
	v_add_u32_e32 v6, v6, v8
	global_load_dwordx2 v[24:25], v6, s[74:75]
	v_add_u32_e32 v6, v6, v8
	global_load_dwordx2 v[26:27], v6, s[74:75]
	v_add_u32_e32 v6, v6, v8
	global_load_dwordx2 v[28:29], v6, s[74:75]
	v_add_u32_e32 v6, v6, v8
	global_load_dwordx2 v[30:31], v6, s[74:75]
	v_add_u32_e32 v6, v6, v8
	global_load_dwordx2 v[32:33], v6, s[74:75]
	v_add_u32_e32 v6, v6, v8
	global_load_dwordx2 v[34:35], v6, s[74:75]
	v_add_u32_e32 v6, v6, v8
	global_load_dwordx2 v[36:37], v6, s[74:75]
	v_add_u32_e32 v6, v6, v8
	global_load_dwordx2 v[38:39], v6, s[74:75]
	v_add_u32_e32 v6, v6, v8
	global_load_dwordx2 v[40:41], v6, s[74:75]
	v_add_u32_e32 v6, v6, v8
	global_load_dwordx2 v[42:43], v6, s[74:75]
	v_add_u32_e32 v6, v6, v8
	global_load_dwordx2 v[44:45], v6, s[74:75]
	v_add_u32_e32 v6, v6, v8
	global_load_dwordx2 v[46:47], v6, s[74:75]
	v_add_u32_e32 v6, v6, v8
	global_load_dwordx2 v[48:49], v6, s[74:75]
	v_add_u32_e32 v6, v6, v8
	global_load_dwordx2 v[50:51], v6, s[74:75]
	v_add_u32_e32 v6, v6, v8
	global_load_dwordx2 v[52:53], v6, s[74:75]
	v_add_u32_e32 v6, v6, v8
	global_load_dwordx2 v[54:55], v6, s[74:75]
	v_add_u32_e32 v6, v6, v8
	global_load_dwordx2 v[56:57], v6, s[74:75]
	v_add_u32_e32 v6, v6, v8
	global_load_dwordx2 v[58:59], v6, s[74:75]
	v_add_u32_e32 v6, v6, v8
	global_load_dwordx2 v[60:61], v6, s[74:75]
	v_add_u32_e32 v6, v6, v8
	global_load_dwordx2 v[62:63], v6, s[74:75]
	v_add_u32_e32 v6, v6, v8
	global_load_dwordx2 v[64:65], v6, s[74:75]
	v_add_u32_e32 v6, v6, v8
	global_load_dwordx2 v[66:67], v6, s[74:75]
	v_add_u32_e32 v6, v6, v8
	global_load_dwordx2 v[68:69], v6, s[74:75]
	v_add_u32_e32 v6, v6, v8
	global_load_dwordx2 v[70:71], v6, s[74:75]
	v_add_u32_e32 v6, v6, v8
	global_load_dwordx2 v[72:73], v6, s[74:75]
	v_add_u32_e32 v6, v6, v8
	global_load_dwordx2 v[74:75], v6, s[74:75]
	v_add_u32_e32 v6, v6, v8
	global_load_dwordx2 v[76:77], v6, s[74:75]
	v_add_u32_e32 v6, v6, v8
	global_load_dwordx2 v[78:79], v6, s[74:75]
	v_add_u32_e32 v6, v6, v8
	global_load_dwordx2 v[80:81], v6, s[74:75]
	v_add_u32_e32 v6, v6, v8
	global_load_dwordx2 v[82:83], v6, s[74:75]
	v_add_u32_e32 v6, v6, v8
	global_load_dwordx2 v[84:85], v6, s[74:75]
	v_add_u32_e32 v6, v6, v8
	global_load_dwordx2 v[86:87], v6, s[74:75]
	v_add_u32_e32 v6, v6, v8
	global_load_dwordx2 v[88:89], v6, s[74:75]
	v_add_u32_e32 v6, v6, v8
	global_load_dwordx2 v[90:91], v6, s[74:75]
	v_add_u32_e32 v6, v6, v8
	global_load_dwordx2 v[92:93], v6, s[74:75]
	v_add_u32_e32 v6, v6, v8
	global_load_dwordx2 v[94:95], v6, s[74:75]
	v_add_u32_e32 v6, v6, v8
	global_load_dwordx2 v[96:97], v6, s[74:75]
	v_add_u32_e32 v6, v6, v8
	global_load_dwordx2 v[98:99], v6, s[74:75]
	v_add_u32_e32 v6, v6, v8
	global_load_dwordx2 v[100:101], v6, s[74:75]
	v_add_u32_e32 v6, v6, v8
	global_load_dwordx2 v[102:103], v6, s[74:75]
	v_add_u32_e32 v6, v6, v8
	global_load_dwordx2 v[104:105], v6, s[74:75]
	v_add_u32_e32 v6, v6, v8
	global_load_dwordx2 v[106:107], v6, s[74:75]
	v_add_u32_e32 v6, v6, v8
	global_load_dwordx2 v[108:109], v6, s[74:75]
	v_add_u32_e32 v6, v6, v8
	s_waitcnt vmcnt(32)
	s_bitcmp1_b32 s28, 0
	s_cbranch_scc0 .Lcs_0
	global_store_dword v7, v13, s[4:5]
.Lcs_0:
	v_add_u32_e32 v7, v7, v10
	v_fma_f32 v13, v14, v13, v15
	s_bitcmp1_b32 s28, 0
	s_cbranch_scc0 .Lcs_1
	global_store_dword v7, v13, s[4:5]
.Lcs_1:
	v_add_u32_e32 v7, v7, v10
	v_fma_f32 v13, v16, v13, v17
	s_bitcmp1_b32 s28, 1
	s_cbranch_scc0 .Lcs_2
	global_store_dword v7, v13, s[4:5]
.Lcs_2:
	v_add_u32_e32 v7, v7, v10
	v_fma_f32 v13, v18, v13, v19
	s_bitcmp1_b32 s28, 1
	s_cbranch_scc0 .Lcs_3
	global_store_dword v7, v13, s[4:5]
.Lcs_3:
	v_add_u32_e32 v7, v7, v10
	v_fma_f32 v13, v20, v13, v21
	s_bitcmp1_b32 s28, 2
	s_cbranch_scc0 .Lcs_4
	global_store_dword v7, v13, s[4:5]
.Lcs_4:
	v_add_u32_e32 v7, v7, v10
	v_fma_f32 v13, v22, v13, v23
	s_bitcmp1_b32 s28, 2
	s_cbranch_scc0 .Lcs_5
	global_store_dword v7, v13, s[4:5]
; __device__ __forceinline__ void carry_phase(const Args& a, int bx) {
;     ...
;         for (int i = 0; i < 32; ++i) { const int j = j0 + i, cj = dir == 0 ? j : NCH - 1 - j; v[i] = tot[(size_t)((b * NCH + cj) * 2 + dir) * LW + c]; }
; #pragma unroll
;         for (int i = 0; i < 32; ++i) { const int j = j0 + i, cj = dir == 0 ? j : NCH - 1 - j; car[(size_t)((b * NCH + cj) * 2 + dir) * LW + c] = hc; hc = v[i].x * hc + v[i].y; }
.Lcs_5:
	v_add_u32_e32 v7, v7, v10
	v_fma_f32 v13, v24, v13, v25
	s_bitcmp1_b32 s28, 3
	s_cbranch_scc0 .Lcs_6
	global_store_dword v7, v13, s[4:5]
.Lcs_6:
	v_add_u32_e32 v7, v7, v10
	v_fma_f32 v13, v26, v13, v27
	s_bitcmp1_b32 s28, 3
	s_cbranch_scc0 .Lcs_7
	global_store_dword v7, v13, s[4:5]
.Lcs_7:
	v_add_u32_e32 v7, v7, v10
	v_fma_f32 v13, v28, v13, v29
	s_bitcmp1_b32 s28, 4
	s_cbranch_scc0 .Lcs_8
	global_store_dword v7, v13, s[4:5]
.Lcs_8:
	v_add_u32_e32 v7, v7, v10
	v_fma_f32 v13, v30, v13, v31
	s_bitcmp1_b32 s28, 4
	s_cbranch_scc0 .Lcs_9
	global_store_dword v7, v13, s[4:5]
.Lcs_9:
	v_add_u32_e32 v7, v7, v10
	v_fma_f32 v13, v32, v13, v33
	s_bitcmp1_b32 s28, 5
	s_cbranch_scc0 .Lcs_10
	global_store_dword v7, v13, s[4:5]
.Lcs_10:
	v_add_u32_e32 v7, v7, v10
	v_fma_f32 v13, v34, v13, v35
	s_bitcmp1_b32 s28, 5
	s_cbranch_scc0 .Lcs_11
	global_store_dword v7, v13, s[4:5]
.Lcs_11:
	v_add_u32_e32 v7, v7, v10
	v_fma_f32 v13, v36, v13, v37
	s_bitcmp1_b32 s28, 6
	s_cbranch_scc0 .Lcs_12
	global_store_dword v7, v13, s[4:5]
.Lcs_12:
	v_add_u32_e32 v7, v7, v10
	v_fma_f32 v13, v38, v13, v39
	s_bitcmp1_b32 s28, 6
	s_cbranch_scc0 .Lcs_13
	global_store_dword v7, v13, s[4:5]
.Lcs_13:
	v_add_u32_e32 v7, v7, v10
	v_fma_f32 v13, v40, v13, v41
	s_bitcmp1_b32 s28, 7
	s_cbranch_scc0 .Lcs_14
	global_store_dword v7, v13, s[4:5]
.Lcs_14:
	v_add_u32_e32 v7, v7, v10
	v_fma_f32 v13, v42, v13, v43
	s_bitcmp1_b32 s28, 7
	s_cbranch_scc0 .Lcs_15
	global_store_dword v7, v13, s[4:5]
.Lcs_15:
	v_add_u32_e32 v7, v7, v10
	v_fma_f32 v13, v44, v13, v45
	global_load_dwordx2 v[110:111], v6, s[74:75]
	v_add_u32_e32 v6, v6, v8
	global_load_dwordx2 v[112:113], v6, s[74:75]
	v_add_u32_e32 v6, v6, v8
	global_load_dwordx2 v[114:115], v6, s[74:75]
	v_add_u32_e32 v6, v6, v8
	global_load_dwordx2 v[116:117], v6, s[74:75]
	v_add_u32_e32 v6, v6, v8
	global_load_dwordx2 v[118:119], v6, s[74:75]
	v_add_u32_e32 v6, v6, v8
	global_load_dwordx2 v[120:121], v6, s[74:75]
	v_add_u32_e32 v6, v6, v8
	global_load_dwordx2 v[122:123], v6, s[74:75]
	v_add_u32_e32 v6, v6, v8
	global_load_dwordx2 v[124:125], v6, s[74:75]
	v_add_u32_e32 v6, v6, v8
	global_load_dwordx2 v[126:127], v6, s[74:75]
	v_add_u32_e32 v6, v6, v8
	global_load_dwordx2 v[128:129], v6, s[74:75]
	v_add_u32_e32 v6, v6, v8
	global_load_dwordx2 v[130:131], v6, s[74:75]
	v_add_u32_e32 v6, v6, v8
	global_load_dwordx2 v[132:133], v6, s[74:75]
	v_add_u32_e32 v6, v6, v8
	global_load_dwordx2 v[134:135], v6, s[74:75]
	v_add_u32_e32 v6, v6, v8
	global_load_dwordx2 v[136:137], v6, s[74:75]
	v_add_u32_e32 v6, v6, v8
	global_load_dwordx2 v[138:139], v6, s[74:75]
	v_add_u32_e32 v6, v6, v8
	global_load_dwordx2 v[140:141], v6, s[74:75]
	v_add_u32_e32 v6, v6, v8
	s_waitcnt vmcnt(32)
	s_bitcmp1_b32 s28, 0
	s_cbranch_scc0 .Lcs_16
	global_store_dword v7, v13, s[4:5]
.Lcs_16:
	v_add_u32_e32 v7, v7, v10
	v_fma_f32 v13, v46, v13, v47
	s_bitcmp1_b32 s28, 0
	s_cbranch_scc0 .Lcs_17
	global_store_dword v7, v13, s[4:5]
.Lcs_17:
	v_add_u32_e32 v7, v7, v10
	v_fma_f32 v13, v48, v13, v49
	s_bitcmp1_b32 s28, 1
	s_cbranch_scc0 .Lcs_18
	global_store_dword v7, v13, s[4:5]
.Lcs_18:
	v_add_u32_e32 v7, v7, v10
	v_fma_f32 v13, v50, v13, v51
	s_bitcmp1_b32 s28, 1
	s_cbranch_scc0 .Lcs_19
	global_store_dword v7, v13, s[4:5]
.Lcs_19:
	v_add_u32_e32 v7, v7, v10
	v_fma_f32 v13, v52, v13, v53
	s_bitcmp1_b32 s28, 2
	s_cbranch_scc0 .Lcs_20
	global_store_dword v7, v13, s[4:5]
.Lcs_20:
	v_add_u32_e32 v7, v7, v10
	v_fma_f32 v13, v54, v13, v55
	s_bitcmp1_b32 s28, 2
	s_cbranch_scc0 .Lcs_21
	global_store_dword v7, v13, s[4:5]
.Lcs_21:
	v_add_u32_e32 v7, v7, v10
	v_fma_f32 v13, v56, v13, v57
	s_bitcmp1_b32 s28, 3
	s_cbranch_scc0 .Lcs_22
	global_store_dword v7, v13, s[4:5]
.Lcs_22:
	v_add_u32_e32 v7, v7, v10
	v_fma_f32 v13, v58, v13, v59
	s_bitcmp1_b32 s28, 3
	s_cbranch_scc0 .Lcs_23
	global_store_dword v7, v13, s[4:5]
.Lcs_23:
	v_add_u32_e32 v7, v7, v10
	v_fma_f32 v13, v60, v13, v61
	s_bitcmp1_b32 s28, 4
	s_cbranch_scc0 .Lcs_24
	global_store_dword v7, v13, s[4:5]
.Lcs_24:
	v_add_u32_e32 v7, v7, v10
	v_fma_f32 v13, v62, v13, v63
	s_bitcmp1_b32 s28, 4
	s_cbranch_scc0 .Lcs_25
	global_store_dword v7, v13, s[4:5]
.Lcs_25:
	v_add_u32_e32 v7, v7, v10
	v_fma_f32 v13, v64, v13, v65
	s_bitcmp1_b32 s28, 5
	s_cbranch_scc0 .Lcs_26
	global_store_dword v7, v13, s[4:5]
.Lcs_26:
	v_add_u32_e32 v7, v7, v10
	v_fma_f32 v13, v66, v13, v67
	s_bitcmp1_b32 s28, 5
	s_cbranch_scc0 .Lcs_27
	global_store_dword v7, v13, s[4:5]
.Lcs_27:
	v_add_u32_e32 v7, v7, v10
	v_fma_f32 v13, v68, v13, v69
	s_bitcmp1_b32 s28, 6
	s_cbranch_scc0 .Lcs_28
	global_store_dword v7, v13, s[4:5]
.Lcs_28:
	v_add_u32_e32 v7, v7, v10
	v_fma_f32 v13, v70, v13, v71
	s_bitcmp1_b32 s28, 6
	s_cbranch_scc0 .Lcs_29
	global_store_dword v7, v13, s[4:5]
.Lcs_29:
	v_add_u32_e32 v7, v7, v10
	v_fma_f32 v13, v72, v13, v73
	s_bitcmp1_b32 s28, 7
	s_cbranch_scc0 .Lcs_30
	global_store_dword v7, v13, s[4:5]
.Lcs_30:
	v_add_u32_e32 v7, v7, v10
	v_fma_f32 v13, v74, v13, v75
	s_bitcmp1_b32 s28, 7
	s_cbranch_scc0 .Lcs_31
	global_store_dword v7, v13, s[4:5]
; __device__ __forceinline__ void carry_phase(const Args& a, int bx) {
;     ...
;         for (int i = 0; i < 32; ++i) { const int j = j0 + i, cj = dir == 0 ? j : NCH - 1 - j; v[i] = tot[(size_t)((b * NCH + cj) * 2 + dir) * LW + c]; }
; #pragma unroll
;         for (int i = 0; i < 32; ++i) { const int j = j0 + i, cj = dir == 0 ? j : NCH - 1 - j; car[(size_t)((b * NCH + cj) * 2 + dir) * LW + c] = hc; hc = v[i].x * hc + v[i].y; }
.Lcs_31:
	v_add_u32_e32 v7, v7, v10
	v_fma_f32 v13, v76, v13, v77
	global_load_dwordx2 v[14:15], v6, s[74:75]
	v_add_u32_e32 v6, v6, v8
	global_load_dwordx2 v[16:17], v6, s[74:75]
	v_add_u32_e32 v6, v6, v8
	global_load_dwordx2 v[18:19], v6, s[74:75]
	v_add_u32_e32 v6, v6, v8
	global_load_dwordx2 v[20:21], v6, s[74:75]
	v_add_u32_e32 v6, v6, v8
	global_load_dwordx2 v[22:23], v6, s[74:75]
	v_add_u32_e32 v6, v6, v8
	global_load_dwordx2 v[24:25], v6, s[74:75]
	v_add_u32_e32 v6, v6, v8
	global_load_dwordx2 v[26:27], v6, s[74:75]
	v_add_u32_e32 v6, v6, v8
	global_load_dwordx2 v[28:29], v6, s[74:75]
	v_add_u32_e32 v6, v6, v8
	global_load_dwordx2 v[30:31], v6, s[74:75]
	v_add_u32_e32 v6, v6, v8
	global_load_dwordx2 v[32:33], v6, s[74:75]
	v_add_u32_e32 v6, v6, v8
	global_load_dwordx2 v[34:35], v6, s[74:75]
	v_add_u32_e32 v6, v6, v8
	global_load_dwordx2 v[36:37], v6, s[74:75]
	v_add_u32_e32 v6, v6, v8
	global_load_dwordx2 v[38:39], v6, s[74:75]
	v_add_u32_e32 v6, v6, v8
	global_load_dwordx2 v[40:41], v6, s[74:75]
	v_add_u32_e32 v6, v6, v8
	global_load_dwordx2 v[42:43], v6, s[74:75]
	v_add_u32_e32 v6, v6, v8
	global_load_dwordx2 v[44:45], v6, s[74:75]
	v_add_u32_e32 v6, v6, v8
	s_waitcnt vmcnt(32)
	s_bitcmp1_b32 s28, 0
	s_cbranch_scc0 .Lcs_32
	global_store_dword v7, v13, s[4:5]
.Lcs_32:
	v_add_u32_e32 v7, v7, v10
	v_fma_f32 v13, v78, v13, v79
	s_bitcmp1_b32 s28, 0
	s_cbranch_scc0 .Lcs_33
	global_store_dword v7, v13, s[4:5]
.Lcs_33:
	v_add_u32_e32 v7, v7, v10
	v_fma_f32 v13, v80, v13, v81
	s_bitcmp1_b32 s28, 1
	s_cbranch_scc0 .Lcs_34
	global_store_dword v7, v13, s[4:5]
.Lcs_34:
	v_add_u32_e32 v7, v7, v10
	v_fma_f32 v13, v82, v13, v83
	s_bitcmp1_b32 s28, 1
	s_cbranch_scc0 .Lcs_35
	global_store_dword v7, v13, s[4:5]
.Lcs_35:
	v_add_u32_e32 v7, v7, v10
	v_fma_f32 v13, v84, v13, v85
	s_bitcmp1_b32 s28, 2
	s_cbranch_scc0 .Lcs_36
	global_store_dword v7, v13, s[4:5]
.Lcs_36:
	v_add_u32_e32 v7, v7, v10
	v_fma_f32 v13, v86, v13, v87
	s_bitcmp1_b32 s28, 2
	s_cbranch_scc0 .Lcs_37
	global_store_dword v7, v13, s[4:5]
.Lcs_37:
	v_add_u32_e32 v7, v7, v10
	v_fma_f32 v13, v88, v13, v89
	s_bitcmp1_b32 s28, 3
	s_cbranch_scc0 .Lcs_38
	global_store_dword v7, v13, s[4:5]
.Lcs_38:
	v_add_u32_e32 v7, v7, v10
	v_fma_f32 v13, v90, v13, v91
	s_bitcmp1_b32 s28, 3
	s_cbranch_scc0 .Lcs_39
	global_store_dword v7, v13, s[4:5]
.Lcs_39:
	v_add_u32_e32 v7, v7, v10
	v_fma_f32 v13, v92, v13, v93
	s_bitcmp1_b32 s28, 4
	s_cbranch_scc0 .Lcs_40
	global_store_dword v7, v13, s[4:5]
.Lcs_40:
	v_add_u32_e32 v7, v7, v10
	v_fma_f32 v13, v94, v13, v95
	s_bitcmp1_b32 s28, 4
	s_cbranch_scc0 .Lcs_41
	global_store_dword v7, v13, s[4:5]
.Lcs_41:
	v_add_u32_e32 v7, v7, v10
	v_fma_f32 v13, v96, v13, v97
	s_bitcmp1_b32 s28, 5
	s_cbranch_scc0 .Lcs_42
	global_store_dword v7, v13, s[4:5]
.Lcs_42:
	v_add_u32_e32 v7, v7, v10
	v_fma_f32 v13, v98, v13, v99
	s_bitcmp1_b32 s28, 5
	s_cbranch_scc0 .Lcs_43
	global_store_dword v7, v13, s[4:5]
.Lcs_43:
	v_add_u32_e32 v7, v7, v10
	v_fma_f32 v13, v100, v13, v101
	s_bitcmp1_b32 s28, 6
	s_cbranch_scc0 .Lcs_44
	global_store_dword v7, v13, s[4:5]
.Lcs_44:
	v_add_u32_e32 v7, v7, v10
	v_fma_f32 v13, v102, v13, v103
	s_bitcmp1_b32 s28, 6
	s_cbranch_scc0 .Lcs_45
	global_store_dword v7, v13, s[4:5]
.Lcs_45:
	v_add_u32_e32 v7, v7, v10
	v_fma_f32 v13, v104, v13, v105
	s_bitcmp1_b32 s28, 7
	s_cbranch_scc0 .Lcs_46
	global_store_dword v7, v13, s[4:5]
.Lcs_46:
	v_add_u32_e32 v7, v7, v10
	v_fma_f32 v13, v106, v13, v107
	s_bitcmp1_b32 s28, 7
	s_cbranch_scc0 .Lcs_47
	global_store_dword v7, v13, s[4:5]
.Lcs_47:
	v_add_u32_e32 v7, v7, v10
	v_fma_f32 v13, v108, v13, v109
	global_load_dwordx2 v[46:47], v6, s[74:75]
	v_add_u32_e32 v6, v6, v8
	global_load_dwordx2 v[48:49], v6, s[74:75]
	v_add_u32_e32 v6, v6, v8
	global_load_dwordx2 v[50:51], v6, s[74:75]
	v_add_u32_e32 v6, v6, v8
	global_load_dwordx2 v[52:53], v6, s[74:75]
	v_add_u32_e32 v6, v6, v8
	global_load_dwordx2 v[54:55], v6, s[74:75]
	v_add_u32_e32 v6, v6, v8
	global_load_dwordx2 v[56:57], v6, s[74:75]
	v_add_u32_e32 v6, v6, v8
	global_load_dwordx2 v[58:59], v6, s[74:75]
	v_add_u32_e32 v6, v6, v8
	global_load_dwordx2 v[60:61], v6, s[74:75]
	v_add_u32_e32 v6, v6, v8
	global_load_dwordx2 v[62:63], v6, s[74:75]
	v_add_u32_e32 v6, v6, v8
	global_load_dwordx2 v[64:65], v6, s[74:75]
	v_add_u32_e32 v6, v6, v8
	global_load_dwordx2 v[66:67], v6, s[74:75]
	v_add_u32_e32 v6, v6, v8
	global_load_dwordx2 v[68:69], v6, s[74:75]
	v_add_u32_e32 v6, v6, v8
	global_load_dwordx2 v[70:71], v6, s[74:75]
	v_add_u32_e32 v6, v6, v8
	global_load_dwordx2 v[72:73], v6, s[74:75]
	v_add_u32_e32 v6, v6, v8
	global_load_dwordx2 v[74:75], v6, s[74:75]
	v_add_u32_e32 v6, v6, v8
	global_load_dwordx2 v[76:77], v6, s[74:75]
	v_add_u32_e32 v6, v6, v8
	s_waitcnt vmcnt(32)
	s_bitcmp1_b32 s28, 0
	s_cbranch_scc0 .Lcs_48
	global_store_dword v7, v13, s[4:5]
; __device__ __forceinline__ void carry_phase(const Args& a, int bx) {
;     ...
;         for (int i = 0; i < 32; ++i) { const int j = j0 + i, cj = dir == 0 ? j : NCH - 1 - j; v[i] = tot[(size_t)((b * NCH + cj) * 2 + dir) * LW + c]; }
; #pragma unroll
;         for (int i = 0; i < 32; ++i) { const int j = j0 + i, cj = dir == 0 ? j : NCH - 1 - j; car[(size_t)((b * NCH + cj) * 2 + dir) * LW + c] = hc; hc = v[i].x * hc + v[i].y; }
.Lcs_48:
	v_add_u32_e32 v7, v7, v10
	v_fma_f32 v13, v110, v13, v111
	s_bitcmp1_b32 s28, 0
	s_cbranch_scc0 .Lcs_49
	global_store_dword v7, v13, s[4:5]
.Lcs_49:
	v_add_u32_e32 v7, v7, v10
	v_fma_f32 v13, v112, v13, v113
	s_bitcmp1_b32 s28, 1
	s_cbranch_scc0 .Lcs_50
	global_store_dword v7, v13, s[4:5]
.Lcs_50:
	v_add_u32_e32 v7, v7, v10
	v_fma_f32 v13, v114, v13, v115
	s_bitcmp1_b32 s28, 1
	s_cbranch_scc0 .Lcs_51
	global_store_dword v7, v13, s[4:5]
.Lcs_51:
	v_add_u32_e32 v7, v7, v10
	v_fma_f32 v13, v116, v13, v117
	s_bitcmp1_b32 s28, 2
	s_cbranch_scc0 .Lcs_52
	global_store_dword v7, v13, s[4:5]
.Lcs_52:
	v_add_u32_e32 v7, v7, v10
	v_fma_f32 v13, v118, v13, v119
	s_bitcmp1_b32 s28, 2
	s_cbranch_scc0 .Lcs_53
	global_store_dword v7, v13, s[4:5]
.Lcs_53:
	v_add_u32_e32 v7, v7, v10
	v_fma_f32 v13, v120, v13, v121
	s_bitcmp1_b32 s28, 3
	s_cbranch_scc0 .Lcs_54
	global_store_dword v7, v13, s[4:5]
.Lcs_54:
	v_add_u32_e32 v7, v7, v10
	v_fma_f32 v13, v122, v13, v123
	s_bitcmp1_b32 s28, 3
	s_cbranch_scc0 .Lcs_55
	global_store_dword v7, v13, s[4:5]
.Lcs_55:
	v_add_u32_e32 v7, v7, v10
	v_fma_f32 v13, v124, v13, v125
	s_bitcmp1_b32 s28, 4
	s_cbranch_scc0 .Lcs_56
	global_store_dword v7, v13, s[4:5]
.Lcs_56:
	v_add_u32_e32 v7, v7, v10
	v_fma_f32 v13, v126, v13, v127
	s_bitcmp1_b32 s28, 4
	s_cbranch_scc0 .Lcs_57
	global_store_dword v7, v13, s[4:5]
.Lcs_57:
	v_add_u32_e32 v7, v7, v10
	v_fma_f32 v13, v128, v13, v129
	s_bitcmp1_b32 s28, 5
	s_cbranch_scc0 .Lcs_58
	global_store_dword v7, v13, s[4:5]
.Lcs_58:
	v_add_u32_e32 v7, v7, v10
	v_fma_f32 v13, v130, v13, v131
	s_bitcmp1_b32 s28, 5
	s_cbranch_scc0 .Lcs_59
	global_store_dword v7, v13, s[4:5]
.Lcs_59:
	v_add_u32_e32 v7, v7, v10
	v_fma_f32 v13, v132, v13, v133
	s_bitcmp1_b32 s28, 6
	s_cbranch_scc0 .Lcs_60
	global_store_dword v7, v13, s[4:5]
.Lcs_60:
	v_add_u32_e32 v7, v7, v10
	v_fma_f32 v13, v134, v13, v135
	s_bitcmp1_b32 s28, 6
	s_cbranch_scc0 .Lcs_61
	global_store_dword v7, v13, s[4:5]
.Lcs_61:
	v_add_u32_e32 v7, v7, v10
	v_fma_f32 v13, v136, v13, v137
	s_bitcmp1_b32 s28, 7
	s_cbranch_scc0 .Lcs_62
	global_store_dword v7, v13, s[4:5]
.Lcs_62:
	v_add_u32_e32 v7, v7, v10
	v_fma_f32 v13, v138, v13, v139
	s_bitcmp1_b32 s28, 7
	s_cbranch_scc0 .Lcs_63
	global_store_dword v7, v13, s[4:5]
.Lcs_63:
	v_add_u32_e32 v7, v7, v10
	v_fma_f32 v13, v140, v13, v141
	global_load_dwordx2 v[78:79], v6, s[74:75]
	v_add_u32_e32 v6, v6, v8
	global_load_dwordx2 v[80:81], v6, s[74:75]
	v_add_u32_e32 v6, v6, v8
	global_load_dwordx2 v[82:83], v6, s[74:75]
	v_add_u32_e32 v6, v6, v8
	global_load_dwordx2 v[84:85], v6, s[74:75]
	v_add_u32_e32 v6, v6, v8
	global_load_dwordx2 v[86:87], v6, s[74:75]
	v_add_u32_e32 v6, v6, v8
	global_load_dwordx2 v[88:89], v6, s[74:75]
	v_add_u32_e32 v6, v6, v8
	global_load_dwordx2 v[90:91], v6, s[74:75]
	v_add_u32_e32 v6, v6, v8
	global_load_dwordx2 v[92:93], v6, s[74:75]
	v_add_u32_e32 v6, v6, v8
	global_load_dwordx2 v[94:95], v6, s[74:75]
	v_add_u32_e32 v6, v6, v8
	global_load_dwordx2 v[96:97], v6, s[74:75]
	v_add_u32_e32 v6, v6, v8
	global_load_dwordx2 v[98:99], v6, s[74:75]
	v_add_u32_e32 v6, v6, v8
	global_load_dwordx2 v[100:101], v6, s[74:75]
	v_add_u32_e32 v6, v6, v8
	global_load_dwordx2 v[102:103], v6, s[74:75]
	v_add_u32_e32 v6, v6, v8
	global_load_dwordx2 v[104:105], v6, s[74:75]
	v_add_u32_e32 v6, v6, v8
	global_load_dwordx2 v[106:107], v6, s[74:75]
	v_add_u32_e32 v6, v6, v8
	global_load_dwordx2 v[108:109], v6, s[74:75]
	v_add_u32_e32 v6, v6, v8
	s_waitcnt vmcnt(32)
	s_bitcmp1_b32 s28, 0
	s_cbranch_scc0 .Lcs_64
	global_store_dword v7, v13, s[4:5]

; __device__ __forceinline__ void carry_phase(const Args& a, int bx) {
;     ...
;         for (int i = 0; i < 32; ++i) { const int j = j0 + i, cj = dir == 0 ? j : NCH - 1 - j; v[i] = tot[(size_t)((b * NCH + cj) * 2 + dir) * LW + c]; }
; #pragma unroll
;         for (int i = 0; i < 32; ++i) { const int j = j0 + i, cj = dir == 0 ? j : NCH - 1 - j; car[(size_t)((b * NCH + cj) * 2 + dir) * LW + c] = hc; hc = v[i].x * hc + v[i].y; }
.Lcs_95:
	v_add_u32_e32 v7, v7, v10
	v_fma_f32 v13, v76, v13, v77
	s_waitcnt vmcnt(16)
	s_bitcmp1_b32 s28, 0
	s_cbranch_scc0 .Lcs_96
	global_store_dword v7, v13, s[4:5]

; __device__ __forceinline__ void carry_phase(const Args& a, int bx) {
;     ...
;         for (int i = 0; i < 32; ++i) { const int j = j0 + i, cj = dir == 0 ? j : NCH - 1 - j; v[i] = tot[(size_t)((b * NCH + cj) * 2 + dir) * LW + c]; }
; #pragma unroll
;         for (int i = 0; i < 32; ++i) { const int j = j0 + i, cj = dir == 0 ? j : NCH - 1 - j; car[(size_t)((b * NCH + cj) * 2 + dir) * LW + c] = hc; hc = v[i].x * hc + v[i].y; }
.Lcs_111:
	v_add_u32_e32 v7, v7, v10
	v_fma_f32 v13, v108, v13, v109
	s_waitcnt vmcnt(0)
	s_bitcmp1_b32 s28, 0
	s_cbranch_scc0 .Lcs_112
	global_store_dword v7, v13, s[4:5]

; __device__ __forceinline__ void carry_phase(const Args& a, int bx) {
;     ...
;         for (int i = 0; i < 32; ++i) { const int j = j0 + i, cj = dir == 0 ? j : NCH - 1 - j; v[i] = tot[(size_t)((b * NCH + cj) * 2 + dir) * LW + c]; }
; #pragma unroll
;         for (int i = 0; i < 32; ++i) { const int j = j0 + i, cj = dir == 0 ? j : NCH - 1 - j; car[(size_t)((b * NCH + cj) * 2 + dir) * LW + c] = hc; hc = v[i].x * hc + v[i].y; }
.Lcs_127:
	v_add_u32_e32 v7, v7, v10
	v_fma_f32 v13, v140, v13, v141
